# scan reads the producers' write-through operands with sc1 loads, no L1 invalidate per round
# speedup vs baseline: 1.0131x; 1.0072x over previous
; DEVINL void rw_stage(const bf16_t* rwbase, int t0, int hd, float* buf, int ht, int nth) {
;     for (int item = ht; item < 7 * TC * 8; item += nth) {
;         const int arr = item / (TC * 8), rem = item - arr * (TC * 8), tt = rem >> 3, c8 = rem & 7;
;         const u32x4 raw = *(const u32x4*)(rwbase + (size_t)arr * T * 512 + (size_t)(t0 + tt) * 512 + hd * 64 + c8 * 8);
; DEVINL void rw_wait_ready(const unsigned* cnt3, unsigned need, int nP) {
;     for (int j = 0; j < nP; ++j)
;         while (__hip_atomic_load(cnt3 + j, __ATOMIC_RELAXED, __HIP_MEMORY_SCOPE_AGENT) < need) __builtin_amdgcn_s_sleep(8);
;     __builtin_amdgcn_fence(__ATOMIC_ACQUIRE, "agent");
;     asm volatile("s_waitcnt vmcnt(0)" ::: "memory");
.LBB0_298:
	s_nop 0
	s_waitcnt vmcnt(0)
	s_lshr_b32 s35, s95, 3
	s_movk_i32 s1, 0x380
	s_mulk_i32 s35, 0x880
	v_cmp_gt_i32_e32 vcc, s1, v146
	v_lshlrev_b32_e32 v8, 3, v146
	s_and_saveexec_b64 s[4:5], vcc
	s_cbranch_execz .LBB0_303
	s_mov_b64 s[6:7], 0
	s_lshl_b32 s66, s0, 1
	v_mov_b32_e32 v9, v8
	v_mov_b32_e32 v10, v146
	s_branch .LBB0_301

; DEVINL float bflo(unsigned u) { return __uint_as_float(u << 16); }
; DEVINL float bfhi(unsigned u) { return __uint_as_float(u & 0xffff0000u); }
; DEVINL float fexp2(float x) { return __builtin_amdgcn_exp2f(x); }
; DEVINL void rw_stage(const bf16_t* rwbase, int t0, int hd, float* buf, int ht, int nth) {
;     for (int item = ht; item < 7 * TC * 8; item += nth) {
;         const int arr = item / (TC * 8), rem = item - arr * (TC * 8), tt = rem >> 3, c8 = rem & 7;
;         const u32x4 raw = *(const u32x4*)(rwbase + (size_t)arr * T * 512 + (size_t)(t0 + tt) * 512 + hd * 64 + c8 * 8);
;         f32x4 lo = {bflo(raw[0]), bfhi(raw[0]), bflo(raw[1]), bfhi(raw[1])}, hi = {bflo(raw[2]), bfhi(raw[2]), bflo(raw[3]), bfhi(raw[3])};
;         if (arr == 1) {
; #pragma unroll
;             for (int j = 0; j < 4; ++j) { lo[j] = fexp2(lo[j]); hi[j] = fexp2(hi[j]); }
;         }
;         float* d = buf + arr * TC * 64 + tt * 64 + c8 * 8;
;         *(f32x4*)d = lo; *(f32x4*)(d + 4) = hi;
;     }
; }
; DEVINL void rw_stage_load(u32x4 (&raw)[4], const bf16_t* rwbase, int t0, int hd, int ht) {
;     const int rem = ht & 127, tt = rem >> 3, c8 = rem & 7;
; #pragma unroll
;     for (int k = 0; k < 4; ++k) {
;         const int arr = (ht >> 7) + 2 * k;
;         if (arr < 7) raw[k] = *(const u32x4*)(rwbase + (size_t)arr * T * 512 + (size_t)(t0 + tt) * 512 + hd * 64 + c8 * 8);
;     }
; }
.LBB0_301:
	v_ashrrev_i32_e32 v0, 31, v10
	v_lshrrev_b32_e32 v0, 25, v0
	v_add_u32_e32 v0, v10, v0
	v_ashrrev_i32_e32 v11, 7, v0
	v_and_b32_e32 v0, 0xffffff80, v0
	v_sub_u32_e32 v0, v10, v0
	v_ashrrev_i32_e32 v12, 3, v0
	v_readlane_b32 s8, v245, 28
	v_readlane_b32 s9, v245, 29
	v_add_u32_e32 v2, s35, v12
	v_ashrrev_i32_e32 v3, 31, v2
	v_mov_b64_e32 v[0:1], s[8:9]
	v_mad_i64_i32 v[0:1], s[8:9], v11, s11, v[0:1]
	v_lshlrev_b64 v[2:3], 10, v[2:3]
	v_lshl_add_u64 v[0:1], v[0:1], 0, v[2:3]
	v_and_b32_e32 v13, 56, v9
	v_lshl_add_u64 v[0:1], v[0:1], 0, s[66:67]
	v_lshlrev_b32_e32 v64, 1, v13
	v_lshl_add_u64 v[0:1], v[0:1], 0, v[64:65]
	global_load_dwordx4 v[4:7], v[0:1], off sc1
	v_and_b32_e32 v14, 0xffffff80, v10
	v_cmp_ne_u32_e32 vcc, s39, v14
	s_waitcnt vmcnt(0)
	v_lshlrev_b32_e32 v0, 16, v4
	v_and_b32_e32 v1, 0xffff0000, v4
	v_lshlrev_b32_e32 v2, 16, v5
	v_and_b32_e32 v3, 0xffff0000, v5
	v_lshlrev_b32_e32 v4, 16, v6
	v_and_b32_e32 v5, 0xffff0000, v6
	v_lshlrev_b32_e32 v6, 16, v7
	v_and_b32_e32 v7, 0xffff0000, v7
	s_and_saveexec_b64 s[8:9], vcc
	s_xor_b64 s[8:9], exec, s[8:9]
	s_andn2_saveexec_b64 s[8:9], s[8:9]
	s_cbranch_execz .LBB0_300
	v_exp_f32_e32 v0, v0
	v_exp_f32_e32 v4, v4
	v_exp_f32_e32 v1, v1
	v_exp_f32_e32 v5, v5
	v_exp_f32_e32 v2, v2
	v_exp_f32_e32 v6, v6
	v_exp_f32_e32 v3, v3
	v_exp_f32_e32 v7, v7
	s_branch .LBB0_300
.LBB0_303:
	s_or_b64 exec, exec, s[4:5]
	v_ashrrev_i32_e32 v150, 6, v146
	v_add_u32_e32 v21, 0xffffff00, v146
	v_lshrrev_b32_e32 v0, 3, v146
	v_cmp_gt_i32_e32 vcc, 4, v150
	v_lshrrev_b32_e32 v22, 7, v21
	v_and_or_b32 v151, v0, 15, s35
	v_and_b32_e32 v16, 56, v8
	s_and_saveexec_b64 s[4:5], vcc
	s_xor_b64 s[4:5], exec, s[4:5]
	v_and_b32_e32 v64, 56, v8
	v_lshrrev_b32_e32 v22, 7, v21
	v_and_or_b32 v151, v0, 15, s35
	s_mov_b32 s1, s67
	v_mov_b32_e32 v152, v64
	v_mov_b64_e32 v[16:17], v[64:65]
	s_or_saveexec_b64 s[4:5], s[4:5]
	v_mov_b32_e32 v64, v65
	v_mov_b32_e32 v66, v65
	v_mov_b32_e32 v67, v65
	v_mov_b64_e32 v[0:1], v[64:65]
	v_mov_b64_e32 v[4:5], v[64:65]
	v_mov_b64_e32 v[8:9], v[64:65]
	v_mov_b64_e32 v[12:13], v[64:65]
	v_mov_b64_e32 v[18:19], s[0:1]
	v_mov_b64_e32 v[2:3], v[66:67]
	v_mov_b64_e32 v[6:7], v[66:67]
	v_mov_b64_e32 v[10:11], v[66:67]
	v_mov_b64_e32 v[14:15], v[66:67]
	s_xor_b64 exec, exec, s[4:5]
	s_cbranch_execz .LBB0_315
	v_or_b32_e32 v0, 16, v151
	v_ashrrev_i32_e32 v1, 31, v0
	v_readlane_b32 s6, v245, 28
	v_lshlrev_b64 v[0:1], 10, v[0:1]
	v_readlane_b32 s7, v245, 29
	s_lshl_b32 s66, s0, 1
	v_lshlrev_b32_e32 v64, 1, v16
	v_lshl_add_u64 v[0:1], s[6:7], 0, v[0:1]
	v_lshl_add_u64 v[0:1], v[0:1], 0, s[66:67]
	v_mov_b32_e32 v4, v65
	v_mov_b32_e32 v5, v65
	v_lshl_add_u64 v[18:19], v[0:1], 0, v[64:65]
	s_movk_i32 s1, 0x380
	v_mov_b32_e32 v6, v65
	v_mov_b32_e32 v7, v65
	v_mov_b64_e32 v[0:1], v[4:5]
	v_cmp_gt_u32_e32 vcc, s1, v21
	v_mul_lo_u32 v12, v22, s11
	v_mov_b64_e32 v[2:3], v[6:7]
	s_and_saveexec_b64 s[6:7], vcc
	s_cbranch_execz .LBB0_308
	v_mov_b32_e32 v13, v65
	v_lshl_add_u64 v[0:1], v[18:19], 0, v[12:13]
	global_load_dwordx4 v[0:3], v[0:1], off sc1
.LBB0_308:
	s_or_b64 exec, exec, s[6:7]
	s_movk_i32 s1, 0x280
	v_cmp_gt_u32_e32 vcc, s1, v21
	s_and_saveexec_b64 s[6:7], vcc
	s_cbranch_execz .LBB0_310
	v_mov_b32_e32 v13, v65
	v_lshl_add_u64 v[4:5], v[18:19], 0, v[12:13]
	v_add_co_u32_e32 v4, vcc, 0x2200000, v4
	s_nop 1
	v_addc_co_u32_e32 v5, vcc, 0, v5, vcc
	global_load_dwordx4 v[4:7], v[4:5], off sc1
.LBB0_310:
	s_or_b64 exec, exec, s[6:7]
	v_mov_b32_e32 v64, v65
	s_movk_i32 s1, 0x180
	v_mov_b32_e32 v66, v65
	v_mov_b32_e32 v67, v65
	v_mov_b64_e32 v[8:9], v[64:65]
	v_cmp_gt_u32_e32 vcc, s1, v21
	v_mov_b64_e32 v[10:11], v[66:67]
	s_and_saveexec_b64 s[6:7], vcc
	s_cbranch_execz .LBB0_312
	v_mov_b32_e32 v13, v65
	v_lshl_add_u64 v[8:9], v[18:19], 0, v[12:13]
	v_add_co_u32_e32 v8, vcc, 0x4400000, v8
	s_nop 1
	v_addc_co_u32_e32 v9, vcc, 0, v9, vcc
	global_load_dwordx4 v[8:11], v[8:9], off sc1
.LBB0_312:
	s_or_b64 exec, exec, s[6:7]
	v_mov_b64_e32 v[12:13], v[64:65]
	v_cmp_gt_u32_e32 vcc, s39, v21
	v_mov_b64_e32 v[14:15], v[66:67]
	s_and_saveexec_b64 s[6:7], vcc
	s_cbranch_execz .LBB0_314
	v_add_co_u32_e32 v12, vcc, 0x6600000, v18
	s_nop 1
	v_addc_co_u32_e32 v13, vcc, 0, v19, vcc
	global_load_dwordx4 v[12:15], v[12:13], off sc1

; DEVINL void rw_stage_load(u32x4 (&raw)[4], const bf16_t* rwbase, int t0, int hd, int ht) {
;     const int rem = ht & 127, tt = rem >> 3, c8 = rem & 7;
; #pragma unroll
;     for (int k = 0; k < 4; ++k) {
;         const int arr = (ht >> 7) + 2 * k;
;         if (arr < 7) raw[k] = *(const u32x4*)(rwbase + (size_t)arr * T * 512 + (size_t)(t0 + tt) * 512 + hd * 64 + c8 * 8);
;     }
; }
.Lsl_p2:
	s_and_saveexec_b64 s[26:27], s[14:15]
	s_cbranch_execz .Lsl_p2_0
	v_lshl_add_u64 v[68:69], v[16:17], 0, v[136:137]
	global_load_dwordx4 v[68:71], v[68:69], off sc1
.Lsl_p2_0:
	s_or_b64 exec, exec, s[26:27]
	s_and_saveexec_b64 s[26:27], s[16:17]
	s_cbranch_execz .Lsl_p2_1
	v_lshl_add_u64 v[72:73], v[16:17], 0, v[138:139]
	global_load_dwordx4 v[72:75], v[72:73], off sc1
.Lsl_p2_1:
	s_or_b64 exec, exec, s[26:27]
	s_and_saveexec_b64 s[26:27], s[18:19]
	s_cbranch_execz .Lsl_p2_2
	v_lshl_add_u64 v[76:77], v[16:17], 0, v[140:141]
	global_load_dwordx4 v[76:79], v[76:77], off sc1
.Lsl_p2_2:
	s_or_b64 exec, exec, s[26:27]
	s_and_saveexec_b64 s[26:27], s[20:21]
	s_cbranch_execz .Lsl_p2_3
	v_lshl_add_u64 v[80:81], v[16:17], 0, v[142:143]
	global_load_dwordx4 v[80:83], v[80:81], off sc1

; DEVINL void rw_stage_load(u32x4 (&raw)[4], const bf16_t* rwbase, int t0, int hd, int ht) {
;     const int rem = ht & 127, tt = rem >> 3, c8 = rem & 7;
; #pragma unroll
;     for (int k = 0; k < 4; ++k) {
;         const int arr = (ht >> 7) + 2 * k;
;         if (arr < 7) raw[k] = *(const u32x4*)(rwbase + (size_t)arr * T * 512 + (size_t)(t0 + tt) * 512 + hd * 64 + c8 * 8);
;     }
; }
.Lsl_p3:
	s_and_saveexec_b64 s[26:27], s[14:15]
	s_cbranch_execz .Lsl_p3_0
	v_lshl_add_u64 v[84:85], v[16:17], 0, v[136:137]
	global_load_dwordx4 v[84:87], v[84:85], off sc1
.Lsl_p3_0:
	s_or_b64 exec, exec, s[26:27]
	s_and_saveexec_b64 s[26:27], s[16:17]
	s_cbranch_execz .Lsl_p3_1
	v_lshl_add_u64 v[88:89], v[16:17], 0, v[138:139]
	global_load_dwordx4 v[88:91], v[88:89], off sc1
.Lsl_p3_1:
	s_or_b64 exec, exec, s[26:27]
	s_and_saveexec_b64 s[26:27], s[18:19]
	s_cbranch_execz .Lsl_p3_2
	v_lshl_add_u64 v[92:93], v[16:17], 0, v[140:141]
	global_load_dwordx4 v[92:95], v[92:93], off sc1
.Lsl_p3_2:
	s_or_b64 exec, exec, s[26:27]
	s_and_saveexec_b64 s[26:27], s[20:21]
	s_cbranch_execz .Lsl_p3_3
	v_lshl_add_u64 v[96:97], v[16:17], 0, v[142:143]
	global_load_dwordx4 v[96:99], v[96:97], off sc1

; DEVINL void rw_stage_load(u32x4 (&raw)[4], const bf16_t* rwbase, int t0, int hd, int ht) {
;     const int rem = ht & 127, tt = rem >> 3, c8 = rem & 7;
; #pragma unroll
;     for (int k = 0; k < 4; ++k) {
;         const int arr = (ht >> 7) + 2 * k;
;         if (arr < 7) raw[k] = *(const u32x4*)(rwbase + (size_t)arr * T * 512 + (size_t)(t0 + tt) * 512 + hd * 64 + c8 * 8);
;     }
; }
.Lsl_p4:
	s_and_saveexec_b64 s[26:27], s[14:15]
	s_cbranch_execz .Lsl_p4_0
	v_lshl_add_u64 v[100:101], v[16:17], 0, v[136:137]
	global_load_dwordx4 v[100:103], v[100:101], off sc1
.Lsl_p4_0:
	s_or_b64 exec, exec, s[26:27]
	s_and_saveexec_b64 s[26:27], s[16:17]
	s_cbranch_execz .Lsl_p4_1
	v_lshl_add_u64 v[104:105], v[16:17], 0, v[138:139]
	global_load_dwordx4 v[104:107], v[104:105], off sc1
.Lsl_p4_1:
	s_or_b64 exec, exec, s[26:27]
	s_and_saveexec_b64 s[26:27], s[18:19]
	s_cbranch_execz .Lsl_p4_2
	v_lshl_add_u64 v[108:109], v[16:17], 0, v[140:141]
	global_load_dwordx4 v[108:111], v[108:109], off sc1
.Lsl_p4_2:
	s_or_b64 exec, exec, s[26:27]
	s_and_saveexec_b64 s[26:27], s[20:21]
	s_cbranch_execz .Lsl_p4_3
	v_lshl_add_u64 v[112:113], v[16:17], 0, v[142:143]
	global_load_dwordx4 v[112:115], v[112:113], off sc1

; DEVINL void rw_wait_ready(const unsigned* cnt3, unsigned need, int nP) {
;     for (int j = 0; j < nP; ++j)
;         while (__hip_atomic_load(cnt3 + j, __ATOMIC_RELAXED, __HIP_MEMORY_SCOPE_AGENT) < need) __builtin_amdgcn_s_sleep(8);
;     __builtin_amdgcn_fence(__ATOMIC_ACQUIRE, "agent");
;     asm volatile("s_waitcnt vmcnt(0)" ::: "memory");
.LBB0_341:
	s_waitcnt lgkmcnt(0)
	s_nop 0
	s_waitcnt vmcnt(0)
	v_mov_b32_e32 v171, s51

; DEVINL void rw_stage_load(u32x4 (&raw)[4], const bf16_t* rwbase, int t0, int hd, int ht) {
;     const int rem = ht & 127, tt = rem >> 3, c8 = rem & 7;
; #pragma unroll
;     for (int k = 0; k < 4; ++k) {
;         const int arr = (ht >> 7) + 2 * k;
;         if (arr < 7) raw[k] = *(const u32x4*)(rwbase + (size_t)arr * T * 512 + (size_t)(t0 + tt) * 512 + hd * 64 + c8 * 8);
;     }
; }
.Lsl_0:
	s_and_saveexec_b64 s[26:27], s[14:15]
	s_cbranch_execz .Lsl_0_0
	v_lshl_add_u64 v[0:1], v[16:17], 0, v[136:137]
	global_load_dwordx4 v[0:3], v[0:1], off sc1
.Lsl_0_0:
	s_or_b64 exec, exec, s[26:27]
	s_and_saveexec_b64 s[26:27], s[16:17]
	s_cbranch_execz .Lsl_0_1
	v_lshl_add_u64 v[4:5], v[16:17], 0, v[138:139]
	global_load_dwordx4 v[4:7], v[4:5], off sc1
.Lsl_0_1:
	s_or_b64 exec, exec, s[26:27]
	s_and_saveexec_b64 s[26:27], s[18:19]
	s_cbranch_execz .Lsl_0_2
	v_lshl_add_u64 v[8:9], v[16:17], 0, v[140:141]
	global_load_dwordx4 v[8:11], v[8:9], off sc1
.Lsl_0_2:
	s_or_b64 exec, exec, s[26:27]
	s_and_saveexec_b64 s[26:27], s[20:21]
	s_cbranch_execz .Lsl_0_3
	v_lshl_add_u64 v[12:13], v[16:17], 0, v[142:143]
	global_load_dwordx4 v[12:15], v[12:13], off sc1
